# in-proj transposed epilogue: neighbour-lane exchange via DPP quad_perm instead of 64 ds_bpermute round trips per tile
# baseline (speedup 1.0000x reference)
; DI unsigned pack2(float a, float b) { f32x2_t v = {a, b}; bf16x2_t r = __builtin_convertvector(v, bf16x2_t); return __builtin_bit_cast(unsigned, r); }
; DI bfu* wsb(const PX& p, size_t off) { return (bfu*)(p.ws + off); }
; template <int EPI, int HM>
; DI void epi256(const PX& p, int l, f32x4 (&acc)[2][2][4][2], int brow, int bcol, int aux, bool src_input) {
;     ...
;           if (EPI == EPI_INPROJ) {
;             if (col0 < 2304) {
;               const bool odd = (fr & 1) != 0;
;               bfu* d = wsb(p, OFF_BIG + B_ZHY) + (size_t)(col0 + (odd ? 4 : 0)) * NTOK + (row & ~1);
; #pragma unroll
;               for (int j = 0; j < 4; j++) {
;                 const float snd = odd ? v[j] : v[4 + j];
;                 const float rcv = __shfl_xor(snd, 1);
;                 const unsigned pr = odd ? pack2(rcv, v[4 + j]) : pack2(v[j], rcv);
;                 *(unsigned*)(d + (size_t)j * NTOK) = pr;
;               }
.LBB0_668:
	s_or_saveexec_b64 s[6:7], s[6:7]
	v_lshlrev_b32_e32 v135, 2, v135
	v_or_b32_e32 v130, v0, v135
	s_mov_b32 s14, 0x12000
	v_mad_i64_i32 v[130:131], s[14:15], v130, s14, 0
	v_readlane_b32 s14, v253, 29
	v_readlane_b32 s15, v253, 30
	v_and_b32_e32 v132, -2, v134
	v_ashrrev_i32_e32 v133, 31, v132
	v_lshl_add_u64 v[130:131], s[14:15], 0, v[130:131]
	s_xor_b64 exec, exec, s[6:7]
	s_cbranch_execz .LBB0_670
	v_cndmask_b32_e64 v138, v122, v126, s[10:11]
	s_nop 1
	v_mov_b32_dpp v138, v138 quad_perm:[1,0,3,2] row_mask:0xf bank_mask:0xf
	v_lshl_add_u64 v[136:137], v[132:133], 1, v[130:131]
	s_mov_b32 s14, 0x12000
	s_waitcnt lgkmcnt(0)
	v_cndmask_b32_e64 v122, v138, v122, s[10:11]
	v_cndmask_b32_e64 v126, v126, v138, s[10:11]
	v_cndmask_b32_e64 v138, v123, v127, s[10:11]
	v_cvt_pk_bf16_f32 v122, v122, v126
	global_store_dword v[136:137], v122, off
	s_nop 1
	v_mov_b32_dpp v122, v138 quad_perm:[1,0,3,2] row_mask:0xf bank_mask:0xf
	v_cndmask_b32_e64 v126, v124, v128, s[10:11]
	s_waitcnt lgkmcnt(0)
	v_cndmask_b32_e64 v123, v122, v123, s[10:11]
	v_cndmask_b32_e64 v122, v127, v122, s[10:11]
	v_cvt_pk_bf16_f32 v127, v123, v122
	v_add_co_u32_e32 v122, vcc, s14, v136
	s_nop 1
	v_addc_co_u32_e32 v123, vcc, 0, v137, vcc
	global_store_dword v[122:123], v127, off
	s_nop 1
	v_mov_b32_dpp v122, v126 quad_perm:[1,0,3,2] row_mask:0xf bank_mask:0xf
	s_waitcnt lgkmcnt(0)
	v_cndmask_b32_e64 v123, v122, v124, s[10:11]
	v_cndmask_b32_e64 v122, v128, v122, s[10:11]
	v_cvt_pk_bf16_f32 v126, v123, v122
	v_add_co_u32_e32 v122, vcc, 0x24000, v136
	v_cndmask_b32_e64 v124, v125, v129, s[10:11]
	s_nop 0
	v_addc_co_u32_e32 v123, vcc, 0, v137, vcc
	global_store_dword v[122:123], v126, off
	s_nop 1
	v_mov_b32_dpp v122, v124 quad_perm:[1,0,3,2] row_mask:0xf bank_mask:0xf
	s_waitcnt lgkmcnt(0)
	v_cndmask_b32_e64 v123, v122, v125, s[10:11]
	v_cndmask_b32_e64 v122, v129, v122, s[10:11]
	v_cvt_pk_bf16_f32 v124, v123, v122
	v_add_co_u32_e32 v122, vcc, 0x36000, v136
	s_nop 1
	v_addc_co_u32_e32 v123, vcc, 0, v137, vcc
	global_store_dword v[122:123], v124, off

; DI unsigned pack2(float a, float b) { f32x2_t v = {a, b}; bf16x2_t r = __builtin_convertvector(v, bf16x2_t); return __builtin_bit_cast(unsigned, r); }
; DI bfu* wsb(const PX& p, size_t off) { return (bfu*)(p.ws + off); }
; template <int EPI, int HM>
; DI void epi256(const PX& p, int l, f32x4 (&acc)[2][2][4][2], int brow, int bcol, int aux, bool src_input) {
;     ...
;           if (EPI == EPI_INPROJ) {
;             if (col0 < 2304) {
;               const bool odd = (fr & 1) != 0;
;               bfu* d = wsb(p, OFF_BIG + B_ZHY) + (size_t)(col0 + (odd ? 4 : 0)) * NTOK + (row & ~1);
; #pragma unroll
;               for (int j = 0; j < 4; j++) {
;                 const float snd = odd ? v[j] : v[4 + j];
;                 const float rcv = __shfl_xor(snd, 1);
;                 const unsigned pr = odd ? pack2(rcv, v[4 + j]) : pack2(v[j], rcv);
;                 *(unsigned*)(d + (size_t)j * NTOK) = pr;
;               }
.LBB0_675:
	s_or_saveexec_b64 s[6:7], s[6:7]
	s_nop 0
	v_and_b32_e32 v122, -2, v126
	v_ashrrev_i32_e32 v123, 31, v122
	s_xor_b64 exec, exec, s[6:7]
	s_cbranch_execz .LBB0_677
	v_cndmask_b32_e64 v127, v114, v118, s[10:11]
	s_nop 1
	v_mov_b32_dpp v127, v127 quad_perm:[1,0,3,2] row_mask:0xf bank_mask:0xf
	v_lshl_add_u64 v[124:125], v[122:123], 1, v[130:131]
	s_mov_b32 s14, 0x12000
	s_waitcnt lgkmcnt(0)
	v_cndmask_b32_e64 v114, v127, v114, s[10:11]
	v_cndmask_b32_e64 v118, v118, v127, s[10:11]
	v_cndmask_b32_e64 v127, v115, v119, s[10:11]
	v_cvt_pk_bf16_f32 v114, v114, v118
	global_store_dword v[124:125], v114, off
	s_nop 1
	v_mov_b32_dpp v114, v127 quad_perm:[1,0,3,2] row_mask:0xf bank_mask:0xf
	v_cndmask_b32_e64 v118, v116, v120, s[10:11]
	s_waitcnt lgkmcnt(0)
	v_cndmask_b32_e64 v115, v114, v115, s[10:11]
	v_cndmask_b32_e64 v114, v119, v114, s[10:11]
	v_cvt_pk_bf16_f32 v119, v115, v114
	v_add_co_u32_e32 v114, vcc, s14, v124
	s_nop 1
	v_addc_co_u32_e32 v115, vcc, 0, v125, vcc
	global_store_dword v[114:115], v119, off
	s_nop 1
	v_mov_b32_dpp v114, v118 quad_perm:[1,0,3,2] row_mask:0xf bank_mask:0xf
	s_waitcnt lgkmcnt(0)
	v_cndmask_b32_e64 v115, v114, v116, s[10:11]
	v_cndmask_b32_e64 v114, v120, v114, s[10:11]
	v_cvt_pk_bf16_f32 v118, v115, v114
	v_add_co_u32_e32 v114, vcc, 0x24000, v124
	v_cndmask_b32_e64 v116, v117, v121, s[10:11]
	s_nop 0
	v_addc_co_u32_e32 v115, vcc, 0, v125, vcc
	global_store_dword v[114:115], v118, off
	s_nop 1
	v_mov_b32_dpp v114, v116 quad_perm:[1,0,3,2] row_mask:0xf bank_mask:0xf
	s_waitcnt lgkmcnt(0)
	v_cndmask_b32_e64 v115, v114, v117, s[10:11]
	v_cndmask_b32_e64 v114, v121, v114, s[10:11]
	v_cvt_pk_bf16_f32 v116, v115, v114
	v_add_co_u32_e32 v114, vcc, 0x36000, v124
	s_nop 1
	v_addc_co_u32_e32 v115, vcc, 0, v125, vcc
	global_store_dword v[114:115], v116, off

; DI unsigned pack2(float a, float b) { f32x2_t v = {a, b}; bf16x2_t r = __builtin_convertvector(v, bf16x2_t); return __builtin_bit_cast(unsigned, r); }
; DI bfu* wsb(const PX& p, size_t off) { return (bfu*)(p.ws + off); }
; template <int EPI, int HM>
; DI void epi256(const PX& p, int l, f32x4 (&acc)[2][2][4][2], int brow, int bcol, int aux, bool src_input) {
;     ...
;           if (EPI == EPI_INPROJ) {
;             if (col0 < 2304) {
;               const bool odd = (fr & 1) != 0;
;               bfu* d = wsb(p, OFF_BIG + B_ZHY) + (size_t)(col0 + (odd ? 4 : 0)) * NTOK + (row & ~1);
; #pragma unroll
;               for (int j = 0; j < 4; j++) {
;                 const float snd = odd ? v[j] : v[4 + j];
;                 const float rcv = __shfl_xor(snd, 1);
;                 const unsigned pr = odd ? pack2(rcv, v[4 + j]) : pack2(v[j], rcv);
;                 *(unsigned*)(d + (size_t)j * NTOK) = pr;
;               }
.LBB0_682:
	s_or_saveexec_b64 s[6:7], s[6:7]
	s_nop 0
	v_and_b32_e32 v114, -2, v118
	v_ashrrev_i32_e32 v115, 31, v114
	s_xor_b64 exec, exec, s[6:7]
	s_cbranch_execz .LBB0_684
	v_cndmask_b32_e64 v119, v106, v110, s[10:11]
	s_nop 1
	v_mov_b32_dpp v119, v119 quad_perm:[1,0,3,2] row_mask:0xf bank_mask:0xf
	v_lshl_add_u64 v[116:117], v[114:115], 1, v[130:131]
	s_mov_b32 s14, 0x12000
	s_waitcnt lgkmcnt(0)
	v_cndmask_b32_e64 v106, v119, v106, s[10:11]
	v_cndmask_b32_e64 v110, v110, v119, s[10:11]
	v_cndmask_b32_e64 v119, v107, v111, s[10:11]
	v_cvt_pk_bf16_f32 v106, v106, v110
	global_store_dword v[116:117], v106, off
	s_nop 1
	v_mov_b32_dpp v106, v119 quad_perm:[1,0,3,2] row_mask:0xf bank_mask:0xf
	v_cndmask_b32_e64 v110, v108, v112, s[10:11]
	s_waitcnt lgkmcnt(0)
	v_cndmask_b32_e64 v107, v106, v107, s[10:11]
	v_cndmask_b32_e64 v106, v111, v106, s[10:11]
	v_cvt_pk_bf16_f32 v111, v107, v106
	v_add_co_u32_e32 v106, vcc, s14, v116
	s_nop 1
	v_addc_co_u32_e32 v107, vcc, 0, v117, vcc
	global_store_dword v[106:107], v111, off
	s_nop 1
	v_mov_b32_dpp v106, v110 quad_perm:[1,0,3,2] row_mask:0xf bank_mask:0xf
	s_waitcnt lgkmcnt(0)
	v_cndmask_b32_e64 v107, v106, v108, s[10:11]
	v_cndmask_b32_e64 v106, v112, v106, s[10:11]
	v_cvt_pk_bf16_f32 v110, v107, v106
	v_add_co_u32_e32 v106, vcc, 0x24000, v116
	v_cndmask_b32_e64 v108, v109, v113, s[10:11]
	s_nop 0
	v_addc_co_u32_e32 v107, vcc, 0, v117, vcc
	global_store_dword v[106:107], v110, off
	s_nop 1
	v_mov_b32_dpp v106, v108 quad_perm:[1,0,3,2] row_mask:0xf bank_mask:0xf
	s_waitcnt lgkmcnt(0)
	v_cndmask_b32_e64 v107, v106, v109, s[10:11]
	v_cndmask_b32_e64 v106, v113, v106, s[10:11]
	v_cvt_pk_bf16_f32 v108, v107, v106
	v_add_co_u32_e32 v106, vcc, 0x36000, v116
	s_nop 1
	v_addc_co_u32_e32 v107, vcc, 0, v117, vcc
	global_store_dword v[106:107], v108, off

; DI unsigned pack2(float a, float b) { f32x2_t v = {a, b}; bf16x2_t r = __builtin_convertvector(v, bf16x2_t); return __builtin_bit_cast(unsigned, r); }
; DI bfu* wsb(const PX& p, size_t off) { return (bfu*)(p.ws + off); }
; template <int EPI, int HM>
; DI void epi256(const PX& p, int l, f32x4 (&acc)[2][2][4][2], int brow, int bcol, int aux, bool src_input) {
;     ...
;           if (EPI == EPI_INPROJ) {
;             if (col0 < 2304) {
;               const bool odd = (fr & 1) != 0;
;               bfu* d = wsb(p, OFF_BIG + B_ZHY) + (size_t)(col0 + (odd ? 4 : 0)) * NTOK + (row & ~1);
; #pragma unroll
;               for (int j = 0; j < 4; j++) {
;                 const float snd = odd ? v[j] : v[4 + j];
;                 const float rcv = __shfl_xor(snd, 1);
;                 const unsigned pr = odd ? pack2(rcv, v[4 + j]) : pack2(v[j], rcv);
;                 *(unsigned*)(d + (size_t)j * NTOK) = pr;
;               }
.LBB0_689:
	s_or_saveexec_b64 s[6:7], s[6:7]
	s_nop 0
	v_and_b32_e32 v106, -2, v110
	v_ashrrev_i32_e32 v107, 31, v106
	s_xor_b64 exec, exec, s[6:7]
	s_cbranch_execz .LBB0_691
	v_cndmask_b32_e64 v111, v98, v102, s[10:11]
	s_nop 1
	v_mov_b32_dpp v111, v111 quad_perm:[1,0,3,2] row_mask:0xf bank_mask:0xf
	v_lshl_add_u64 v[108:109], v[106:107], 1, v[130:131]
	s_mov_b32 s14, 0x12000
	s_waitcnt lgkmcnt(0)
	v_cndmask_b32_e64 v98, v111, v98, s[10:11]
	v_cndmask_b32_e64 v102, v102, v111, s[10:11]
	v_cndmask_b32_e64 v111, v99, v103, s[10:11]
	v_cvt_pk_bf16_f32 v98, v98, v102
	global_store_dword v[108:109], v98, off
	s_nop 1
	v_mov_b32_dpp v98, v111 quad_perm:[1,0,3,2] row_mask:0xf bank_mask:0xf
	v_cndmask_b32_e64 v102, v100, v104, s[10:11]
	s_waitcnt lgkmcnt(0)
	v_cndmask_b32_e64 v99, v98, v99, s[10:11]
	v_cndmask_b32_e64 v98, v103, v98, s[10:11]
	v_cvt_pk_bf16_f32 v103, v99, v98
	v_add_co_u32_e32 v98, vcc, s14, v108
	s_nop 1
	v_addc_co_u32_e32 v99, vcc, 0, v109, vcc
	global_store_dword v[98:99], v103, off
	s_nop 1
	v_mov_b32_dpp v98, v102 quad_perm:[1,0,3,2] row_mask:0xf bank_mask:0xf
	s_waitcnt lgkmcnt(0)
	v_cndmask_b32_e64 v99, v98, v100, s[10:11]
	v_cndmask_b32_e64 v98, v104, v98, s[10:11]
	v_cvt_pk_bf16_f32 v102, v99, v98
	v_add_co_u32_e32 v98, vcc, 0x24000, v108
	v_cndmask_b32_e64 v100, v101, v105, s[10:11]
	s_nop 0
	v_addc_co_u32_e32 v99, vcc, 0, v109, vcc
	global_store_dword v[98:99], v102, off
	s_nop 1
	v_mov_b32_dpp v98, v100 quad_perm:[1,0,3,2] row_mask:0xf bank_mask:0xf
	s_waitcnt lgkmcnt(0)
	v_cndmask_b32_e64 v99, v98, v101, s[10:11]
	v_cndmask_b32_e64 v98, v105, v98, s[10:11]
	v_cvt_pk_bf16_f32 v100, v99, v98
	v_add_co_u32_e32 v98, vcc, 0x36000, v108
	s_nop 1
	v_addc_co_u32_e32 v99, vcc, 0, v109, vcc
	global_store_dword v[98:99], v100, off

; DI unsigned pack2(float a, float b) { f32x2_t v = {a, b}; bf16x2_t r = __builtin_convertvector(v, bf16x2_t); return __builtin_bit_cast(unsigned, r); }
; DI bfu* wsb(const PX& p, size_t off) { return (bfu*)(p.ws + off); }
; template <int EPI, int HM>
; DI void epi256(const PX& p, int l, f32x4 (&acc)[2][2][4][2], int brow, int bcol, int aux, bool src_input) {
;     ...
;           if (EPI == EPI_INPROJ) {
;             if (col0 < 2304) {
;               const bool odd = (fr & 1) != 0;
;               bfu* d = wsb(p, OFF_BIG + B_ZHY) + (size_t)(col0 + (odd ? 4 : 0)) * NTOK + (row & ~1);
; #pragma unroll
;               for (int j = 0; j < 4; j++) {
;                 const float snd = odd ? v[j] : v[4 + j];
;                 const float rcv = __shfl_xor(snd, 1);
;                 const unsigned pr = odd ? pack2(rcv, v[4 + j]) : pack2(v[j], rcv);
;                 *(unsigned*)(d + (size_t)j * NTOK) = pr;
;               }
.LBB0_696:
	s_or_saveexec_b64 s[14:15], s[14:15]
	s_nop 0
	v_or_b32_e32 v98, v102, v135
	s_mov_b32 s16, 0x12000
	v_mad_i64_i32 v[98:99], s[16:17], v98, s16, 0
	v_readlane_b32 s16, v253, 29
	v_readlane_b32 s17, v253, 30
	s_nop 1
	v_lshl_add_u64 v[98:99], s[16:17], 0, v[98:99]
	s_xor_b64 exec, exec, s[14:15]
	s_cbranch_execz .LBB0_698
	v_cndmask_b32_e64 v102, v90, v94, s[10:11]
	s_nop 1
	v_mov_b32_dpp v102, v102 quad_perm:[1,0,3,2] row_mask:0xf bank_mask:0xf
	v_lshl_add_u64 v[100:101], v[132:133], 1, v[98:99]
	s_mov_b32 s16, 0x12000
	s_waitcnt lgkmcnt(0)
	v_cndmask_b32_e64 v90, v102, v90, s[10:11]
	v_cndmask_b32_e64 v94, v94, v102, s[10:11]
	v_cndmask_b32_e64 v102, v91, v95, s[10:11]
	v_cvt_pk_bf16_f32 v90, v90, v94
	global_store_dword v[100:101], v90, off
	s_nop 1
	v_mov_b32_dpp v90, v102 quad_perm:[1,0,3,2] row_mask:0xf bank_mask:0xf
	v_cndmask_b32_e64 v94, v92, v96, s[10:11]
	s_waitcnt lgkmcnt(0)
	v_cndmask_b32_e64 v91, v90, v91, s[10:11]
	v_cndmask_b32_e64 v90, v95, v90, s[10:11]
	v_cvt_pk_bf16_f32 v95, v91, v90
	v_add_co_u32_e32 v90, vcc, s16, v100
	s_nop 1
	v_addc_co_u32_e32 v91, vcc, 0, v101, vcc
	global_store_dword v[90:91], v95, off
	s_nop 1
	v_mov_b32_dpp v90, v94 quad_perm:[1,0,3,2] row_mask:0xf bank_mask:0xf
	s_waitcnt lgkmcnt(0)
	v_cndmask_b32_e64 v91, v90, v92, s[10:11]
	v_cndmask_b32_e64 v90, v96, v90, s[10:11]
	v_cvt_pk_bf16_f32 v94, v91, v90
	v_add_co_u32_e32 v90, vcc, 0x24000, v100
	v_cndmask_b32_e64 v92, v93, v97, s[10:11]
	s_nop 0
	v_addc_co_u32_e32 v91, vcc, 0, v101, vcc
	global_store_dword v[90:91], v94, off
	s_nop 1
	v_mov_b32_dpp v90, v92 quad_perm:[1,0,3,2] row_mask:0xf bank_mask:0xf
	s_waitcnt lgkmcnt(0)
	v_cndmask_b32_e64 v91, v90, v93, s[10:11]
	v_cndmask_b32_e64 v90, v97, v90, s[10:11]
	v_cvt_pk_bf16_f32 v92, v91, v90
	v_add_co_u32_e32 v90, vcc, 0x36000, v100
	s_nop 1
	v_addc_co_u32_e32 v91, vcc, 0, v101, vcc
	global_store_dword v[90:91], v92, off

; DI unsigned pack2(float a, float b) { f32x2_t v = {a, b}; bf16x2_t r = __builtin_convertvector(v, bf16x2_t); return __builtin_bit_cast(unsigned, r); }
; DI bfu* wsb(const PX& p, size_t off) { return (bfu*)(p.ws + off); }
; template <int EPI, int HM>
; DI void epi256(const PX& p, int l, f32x4 (&acc)[2][2][4][2], int brow, int bcol, int aux, bool src_input) {
;     ...
;           if (EPI == EPI_INPROJ) {
;             if (col0 < 2304) {
;               const bool odd = (fr & 1) != 0;
;               bfu* d = wsb(p, OFF_BIG + B_ZHY) + (size_t)(col0 + (odd ? 4 : 0)) * NTOK + (row & ~1);
; #pragma unroll
;               for (int j = 0; j < 4; j++) {
;                 const float snd = odd ? v[j] : v[4 + j];
;                 const float rcv = __shfl_xor(snd, 1);
;                 const unsigned pr = odd ? pack2(rcv, v[4 + j]) : pack2(v[j], rcv);
;                 *(unsigned*)(d + (size_t)j * NTOK) = pr;
;               }
.LBB0_703:
	s_andn2_saveexec_b64 s[14:15], s[14:15]
	s_cbranch_execz .LBB0_705
	v_cndmask_b32_e64 v92, v82, v86, s[10:11]
	s_nop 1
	v_mov_b32_dpp v92, v92 quad_perm:[1,0,3,2] row_mask:0xf bank_mask:0xf
	v_lshl_add_u64 v[90:91], v[122:123], 1, v[98:99]
	s_mov_b32 s16, 0x12000
	s_waitcnt lgkmcnt(0)
	v_cndmask_b32_e64 v82, v92, v82, s[10:11]
	v_cndmask_b32_e64 v86, v86, v92, s[10:11]
	v_cndmask_b32_e64 v92, v83, v87, s[10:11]
	v_cvt_pk_bf16_f32 v82, v82, v86
	global_store_dword v[90:91], v82, off
	s_nop 1
	v_mov_b32_dpp v82, v92 quad_perm:[1,0,3,2] row_mask:0xf bank_mask:0xf
	v_cndmask_b32_e64 v86, v84, v88, s[10:11]
	s_waitcnt lgkmcnt(0)
	v_cndmask_b32_e64 v83, v82, v83, s[10:11]
	v_cndmask_b32_e64 v82, v87, v82, s[10:11]
	v_cvt_pk_bf16_f32 v87, v83, v82
	v_add_co_u32_e32 v82, vcc, s16, v90
	s_nop 1
	v_addc_co_u32_e32 v83, vcc, 0, v91, vcc
	global_store_dword v[82:83], v87, off
	s_nop 1
	v_mov_b32_dpp v82, v86 quad_perm:[1,0,3,2] row_mask:0xf bank_mask:0xf
	s_waitcnt lgkmcnt(0)
	v_cndmask_b32_e64 v83, v82, v84, s[10:11]
	v_cndmask_b32_e64 v82, v88, v82, s[10:11]
	v_cvt_pk_bf16_f32 v86, v83, v82
	v_add_co_u32_e32 v82, vcc, 0x24000, v90
	v_cndmask_b32_e64 v84, v85, v89, s[10:11]
	s_nop 0
	v_addc_co_u32_e32 v83, vcc, 0, v91, vcc
	global_store_dword v[82:83], v86, off
	s_nop 1
	v_mov_b32_dpp v82, v84 quad_perm:[1,0,3,2] row_mask:0xf bank_mask:0xf
	s_waitcnt lgkmcnt(0)
	v_cndmask_b32_e64 v83, v82, v85, s[10:11]
	v_cndmask_b32_e64 v82, v89, v82, s[10:11]
	v_cvt_pk_bf16_f32 v84, v83, v82
	v_add_co_u32_e32 v82, vcc, 0x36000, v90
	s_nop 1
	v_addc_co_u32_e32 v83, vcc, 0, v91, vcc
	global_store_dword v[82:83], v84, off

; DI unsigned pack2(float a, float b) { f32x2_t v = {a, b}; bf16x2_t r = __builtin_convertvector(v, bf16x2_t); return __builtin_bit_cast(unsigned, r); }
; DI bfu* wsb(const PX& p, size_t off) { return (bfu*)(p.ws + off); }
; template <int EPI, int HM>
; DI void epi256(const PX& p, int l, f32x4 (&acc)[2][2][4][2], int brow, int bcol, int aux, bool src_input) {
;     ...
;           if (EPI == EPI_INPROJ) {
;             if (col0 < 2304) {
;               const bool odd = (fr & 1) != 0;
;               bfu* d = wsb(p, OFF_BIG + B_ZHY) + (size_t)(col0 + (odd ? 4 : 0)) * NTOK + (row & ~1);
; #pragma unroll
;               for (int j = 0; j < 4; j++) {
;                 const float snd = odd ? v[j] : v[4 + j];
;                 const float rcv = __shfl_xor(snd, 1);
;                 const unsigned pr = odd ? pack2(rcv, v[4 + j]) : pack2(v[j], rcv);
;                 *(unsigned*)(d + (size_t)j * NTOK) = pr;
;               }
.LBB0_710:
	s_andn2_saveexec_b64 s[14:15], s[14:15]
	s_cbranch_execz .LBB0_712
	v_cndmask_b32_e64 v84, v74, v78, s[10:11]
	s_nop 1
	v_mov_b32_dpp v84, v84 quad_perm:[1,0,3,2] row_mask:0xf bank_mask:0xf
	v_lshl_add_u64 v[82:83], v[114:115], 1, v[98:99]
	s_mov_b32 s16, 0x12000
	s_waitcnt lgkmcnt(0)
	v_cndmask_b32_e64 v74, v84, v74, s[10:11]
	v_cndmask_b32_e64 v78, v78, v84, s[10:11]
	v_cndmask_b32_e64 v84, v75, v79, s[10:11]
	v_cvt_pk_bf16_f32 v74, v74, v78
	global_store_dword v[82:83], v74, off
	s_nop 1
	v_mov_b32_dpp v74, v84 quad_perm:[1,0,3,2] row_mask:0xf bank_mask:0xf
	v_cndmask_b32_e64 v78, v76, v80, s[10:11]
	s_waitcnt lgkmcnt(0)
	v_cndmask_b32_e64 v75, v74, v75, s[10:11]
	v_cndmask_b32_e64 v74, v79, v74, s[10:11]
	v_cvt_pk_bf16_f32 v79, v75, v74
	v_add_co_u32_e32 v74, vcc, s16, v82
	s_nop 1
	v_addc_co_u32_e32 v75, vcc, 0, v83, vcc
	global_store_dword v[74:75], v79, off
	s_nop 1
	v_mov_b32_dpp v74, v78 quad_perm:[1,0,3,2] row_mask:0xf bank_mask:0xf
	s_waitcnt lgkmcnt(0)
	v_cndmask_b32_e64 v75, v74, v76, s[10:11]
	v_cndmask_b32_e64 v74, v80, v74, s[10:11]
	v_cvt_pk_bf16_f32 v78, v75, v74
	v_add_co_u32_e32 v74, vcc, 0x24000, v82
	v_cndmask_b32_e64 v76, v77, v81, s[10:11]
	s_nop 0
	v_addc_co_u32_e32 v75, vcc, 0, v83, vcc
	global_store_dword v[74:75], v78, off
	s_nop 1
	v_mov_b32_dpp v74, v76 quad_perm:[1,0,3,2] row_mask:0xf bank_mask:0xf
	s_waitcnt lgkmcnt(0)
	v_cndmask_b32_e64 v75, v74, v77, s[10:11]
	v_cndmask_b32_e64 v74, v81, v74, s[10:11]
	v_cvt_pk_bf16_f32 v76, v75, v74
	v_add_co_u32_e32 v74, vcc, 0x36000, v82
	s_nop 1
	v_addc_co_u32_e32 v75, vcc, 0, v83, vcc
	global_store_dword v[74:75], v76, off

; DI unsigned pack2(float a, float b) { f32x2_t v = {a, b}; bf16x2_t r = __builtin_convertvector(v, bf16x2_t); return __builtin_bit_cast(unsigned, r); }
; DI bfu* wsb(const PX& p, size_t off) { return (bfu*)(p.ws + off); }
; template <int EPI, int HM>
; DI void epi256(const PX& p, int l, f32x4 (&acc)[2][2][4][2], int brow, int bcol, int aux, bool src_input) {
;     ...
;           if (EPI == EPI_INPROJ) {
;             if (col0 < 2304) {
;               const bool odd = (fr & 1) != 0;
;               bfu* d = wsb(p, OFF_BIG + B_ZHY) + (size_t)(col0 + (odd ? 4 : 0)) * NTOK + (row & ~1);
; #pragma unroll
;               for (int j = 0; j < 4; j++) {
;                 const float snd = odd ? v[j] : v[4 + j];
;                 const float rcv = __shfl_xor(snd, 1);
;                 const unsigned pr = odd ? pack2(rcv, v[4 + j]) : pack2(v[j], rcv);
;                 *(unsigned*)(d + (size_t)j * NTOK) = pr;
;               }
.LBB0_717:
	s_andn2_saveexec_b64 s[14:15], s[14:15]
	s_cbranch_execz .LBB0_719
	v_cndmask_b32_e64 v76, v66, v70, s[10:11]
	s_nop 1
	v_mov_b32_dpp v76, v76 quad_perm:[1,0,3,2] row_mask:0xf bank_mask:0xf
	v_lshl_add_u64 v[74:75], v[106:107], 1, v[98:99]
	s_mov_b32 s16, 0x12000
	s_waitcnt lgkmcnt(0)
	v_cndmask_b32_e64 v66, v76, v66, s[10:11]
	v_cndmask_b32_e64 v70, v70, v76, s[10:11]
	v_cndmask_b32_e64 v76, v67, v71, s[10:11]
	v_cvt_pk_bf16_f32 v66, v66, v70
	global_store_dword v[74:75], v66, off
	s_nop 1
	v_mov_b32_dpp v66, v76 quad_perm:[1,0,3,2] row_mask:0xf bank_mask:0xf
	v_cndmask_b32_e64 v70, v68, v72, s[10:11]
	s_waitcnt lgkmcnt(0)
	v_cndmask_b32_e64 v67, v66, v67, s[10:11]
	v_cndmask_b32_e64 v66, v71, v66, s[10:11]
	v_cvt_pk_bf16_f32 v71, v67, v66
	v_add_co_u32_e32 v66, vcc, s16, v74
	s_nop 1
	v_addc_co_u32_e32 v67, vcc, 0, v75, vcc
	global_store_dword v[66:67], v71, off
	s_nop 1
	v_mov_b32_dpp v66, v70 quad_perm:[1,0,3,2] row_mask:0xf bank_mask:0xf
	s_waitcnt lgkmcnt(0)
	v_cndmask_b32_e64 v67, v66, v68, s[10:11]
	v_cndmask_b32_e64 v66, v72, v66, s[10:11]
	v_cvt_pk_bf16_f32 v70, v67, v66
	v_add_co_u32_e32 v66, vcc, 0x24000, v74
	v_cndmask_b32_e64 v68, v69, v73, s[10:11]
	s_nop 0
	v_addc_co_u32_e32 v67, vcc, 0, v75, vcc
	global_store_dword v[66:67], v70, off
	s_nop 1
	v_mov_b32_dpp v66, v68 quad_perm:[1,0,3,2] row_mask:0xf bank_mask:0xf
	s_waitcnt lgkmcnt(0)
	v_cndmask_b32_e64 v67, v66, v69, s[10:11]
	v_cndmask_b32_e64 v66, v73, v66, s[10:11]
	v_cvt_pk_bf16_f32 v68, v67, v66
	v_add_co_u32_e32 v66, vcc, 0x36000, v74
	s_nop 1
	v_addc_co_u32_e32 v67, vcc, 0, v75, vcc
	global_store_dword v[66:67], v68, off

; DI unsigned pack2(float a, float b) { f32x2_t v = {a, b}; bf16x2_t r = __builtin_convertvector(v, bf16x2_t); return __builtin_bit_cast(unsigned, r); }
; DI bfu* wsb(const PX& p, size_t off) { return (bfu*)(p.ws + off); }
; template <int EPI, int HM>
; DI void epi256(const PX& p, int l, f32x4 (&acc)[2][2][4][2], int brow, int bcol, int aux, bool src_input) {
;     ...
;           if (EPI == EPI_INPROJ) {
;             if (col0 < 2304) {
;               const bool odd = (fr & 1) != 0;
;               bfu* d = wsb(p, OFF_BIG + B_ZHY) + (size_t)(col0 + (odd ? 4 : 0)) * NTOK + (row & ~1);
; #pragma unroll
;               for (int j = 0; j < 4; j++) {
;                 const float snd = odd ? v[j] : v[4 + j];
;                 const float rcv = __shfl_xor(snd, 1);
;                 const unsigned pr = odd ? pack2(rcv, v[4 + j]) : pack2(v[j], rcv);
;                 *(unsigned*)(d + (size_t)j * NTOK) = pr;
;               }
.LBB0_724:
	s_or_saveexec_b64 s[14:15], s[14:15]
	s_nop 0
	v_and_b32_e32 v66, -2, v70
	v_ashrrev_i32_e32 v67, 31, v66
	s_xor_b64 exec, exec, s[14:15]
	s_cbranch_execz .LBB0_726
	v_cndmask_b32_e64 v71, v58, v62, s[10:11]
	s_nop 1
	v_mov_b32_dpp v71, v71 quad_perm:[1,0,3,2] row_mask:0xf bank_mask:0xf
	v_lshl_add_u64 v[68:69], v[66:67], 1, v[130:131]
	s_mov_b32 s16, 0x12000
	s_waitcnt lgkmcnt(0)
	v_cndmask_b32_e64 v58, v71, v58, s[10:11]
	v_cndmask_b32_e64 v62, v62, v71, s[10:11]
	v_cndmask_b32_e64 v71, v59, v63, s[10:11]
	v_cvt_pk_bf16_f32 v58, v58, v62
	global_store_dword v[68:69], v58, off
	s_nop 1
	v_mov_b32_dpp v58, v71 quad_perm:[1,0,3,2] row_mask:0xf bank_mask:0xf
	v_cndmask_b32_e64 v62, v60, v64, s[10:11]
	s_waitcnt lgkmcnt(0)
	v_cndmask_b32_e64 v59, v58, v59, s[10:11]
	v_cndmask_b32_e64 v58, v63, v58, s[10:11]
	v_cvt_pk_bf16_f32 v63, v59, v58
	v_add_co_u32_e32 v58, vcc, s16, v68
	s_nop 1
	v_addc_co_u32_e32 v59, vcc, 0, v69, vcc
	global_store_dword v[58:59], v63, off
	s_nop 1
	v_mov_b32_dpp v58, v62 quad_perm:[1,0,3,2] row_mask:0xf bank_mask:0xf
	s_waitcnt lgkmcnt(0)
	v_cndmask_b32_e64 v59, v58, v60, s[10:11]
	v_cndmask_b32_e64 v58, v64, v58, s[10:11]
	v_cvt_pk_bf16_f32 v62, v59, v58
	v_add_co_u32_e32 v58, vcc, 0x24000, v68
	v_cndmask_b32_e64 v60, v61, v65, s[10:11]
	s_nop 0
	v_addc_co_u32_e32 v59, vcc, 0, v69, vcc
	global_store_dword v[58:59], v62, off
	s_nop 1
	v_mov_b32_dpp v58, v60 quad_perm:[1,0,3,2] row_mask:0xf bank_mask:0xf
	s_waitcnt lgkmcnt(0)
	v_cndmask_b32_e64 v59, v58, v61, s[10:11]
	v_cndmask_b32_e64 v58, v65, v58, s[10:11]
	v_cvt_pk_bf16_f32 v60, v59, v58
	v_add_co_u32_e32 v58, vcc, 0x36000, v68
	s_nop 1
	v_addc_co_u32_e32 v59, vcc, 0, v69, vcc
	global_store_dword v[58:59], v60, off

; DI unsigned pack2(float a, float b) { f32x2_t v = {a, b}; bf16x2_t r = __builtin_convertvector(v, bf16x2_t); return __builtin_bit_cast(unsigned, r); }
; DI bfu* wsb(const PX& p, size_t off) { return (bfu*)(p.ws + off); }
; template <int EPI, int HM>
; DI void epi256(const PX& p, int l, f32x4 (&acc)[2][2][4][2], int brow, int bcol, int aux, bool src_input) {
;     ...
;           if (EPI == EPI_INPROJ) {
;             if (col0 < 2304) {
;               const bool odd = (fr & 1) != 0;
;               bfu* d = wsb(p, OFF_BIG + B_ZHY) + (size_t)(col0 + (odd ? 4 : 0)) * NTOK + (row & ~1);
; #pragma unroll
;               for (int j = 0; j < 4; j++) {
;                 const float snd = odd ? v[j] : v[4 + j];
;                 const float rcv = __shfl_xor(snd, 1);
;                 const unsigned pr = odd ? pack2(rcv, v[4 + j]) : pack2(v[j], rcv);
;                 *(unsigned*)(d + (size_t)j * NTOK) = pr;
;               }
.LBB0_731:
	s_or_saveexec_b64 s[14:15], s[14:15]
	s_nop 0
	v_and_b32_e32 v58, -2, v62
	v_ashrrev_i32_e32 v59, 31, v58
	s_xor_b64 exec, exec, s[14:15]
	s_cbranch_execz .LBB0_733
	v_cndmask_b32_e64 v63, v50, v54, s[10:11]
	s_nop 1
	v_mov_b32_dpp v63, v63 quad_perm:[1,0,3,2] row_mask:0xf bank_mask:0xf
	v_lshl_add_u64 v[60:61], v[58:59], 1, v[130:131]
	s_mov_b32 s16, 0x12000
	s_waitcnt lgkmcnt(0)
	v_cndmask_b32_e64 v50, v63, v50, s[10:11]
	v_cndmask_b32_e64 v54, v54, v63, s[10:11]
	v_cndmask_b32_e64 v63, v51, v55, s[10:11]
	v_cvt_pk_bf16_f32 v50, v50, v54
	global_store_dword v[60:61], v50, off
	s_nop 1
	v_mov_b32_dpp v50, v63 quad_perm:[1,0,3,2] row_mask:0xf bank_mask:0xf
	v_cndmask_b32_e64 v54, v52, v56, s[10:11]
	s_waitcnt lgkmcnt(0)
	v_cndmask_b32_e64 v51, v50, v51, s[10:11]
	v_cndmask_b32_e64 v50, v55, v50, s[10:11]
	v_cvt_pk_bf16_f32 v55, v51, v50
	v_add_co_u32_e32 v50, vcc, s16, v60
	s_nop 1
	v_addc_co_u32_e32 v51, vcc, 0, v61, vcc
	global_store_dword v[50:51], v55, off
	s_nop 1
	v_mov_b32_dpp v50, v54 quad_perm:[1,0,3,2] row_mask:0xf bank_mask:0xf
	s_waitcnt lgkmcnt(0)
	v_cndmask_b32_e64 v51, v50, v52, s[10:11]
	v_cndmask_b32_e64 v50, v56, v50, s[10:11]
	v_cvt_pk_bf16_f32 v54, v51, v50
	v_add_co_u32_e32 v50, vcc, 0x24000, v60
	v_cndmask_b32_e64 v52, v53, v57, s[10:11]
	s_nop 0
	v_addc_co_u32_e32 v51, vcc, 0, v61, vcc
	global_store_dword v[50:51], v54, off
	s_nop 1
	v_mov_b32_dpp v50, v52 quad_perm:[1,0,3,2] row_mask:0xf bank_mask:0xf
	s_waitcnt lgkmcnt(0)
	v_cndmask_b32_e64 v51, v50, v53, s[10:11]
	v_cndmask_b32_e64 v50, v57, v50, s[10:11]
	v_cvt_pk_bf16_f32 v52, v51, v50
	v_add_co_u32_e32 v50, vcc, 0x36000, v60
	s_nop 1
	v_addc_co_u32_e32 v51, vcc, 0, v61, vcc
	global_store_dword v[50:51], v52, off

; DI unsigned pack2(float a, float b) { f32x2_t v = {a, b}; bf16x2_t r = __builtin_convertvector(v, bf16x2_t); return __builtin_bit_cast(unsigned, r); }
; DI bfu* wsb(const PX& p, size_t off) { return (bfu*)(p.ws + off); }
; template <int EPI, int HM>
; DI void epi256(const PX& p, int l, f32x4 (&acc)[2][2][4][2], int brow, int bcol, int aux, bool src_input) {
;     ...
;           if (EPI == EPI_INPROJ) {
;             if (col0 < 2304) {
;               const bool odd = (fr & 1) != 0;
;               bfu* d = wsb(p, OFF_BIG + B_ZHY) + (size_t)(col0 + (odd ? 4 : 0)) * NTOK + (row & ~1);
; #pragma unroll
;               for (int j = 0; j < 4; j++) {
;                 const float snd = odd ? v[j] : v[4 + j];
;                 const float rcv = __shfl_xor(snd, 1);
;                 const unsigned pr = odd ? pack2(rcv, v[4 + j]) : pack2(v[j], rcv);
;                 *(unsigned*)(d + (size_t)j * NTOK) = pr;
;               }
.LBB0_738:
	s_or_saveexec_b64 s[14:15], s[14:15]
	s_nop 0
	v_and_b32_e32 v50, -2, v54
	v_ashrrev_i32_e32 v51, 31, v50
	s_xor_b64 exec, exec, s[14:15]
	s_cbranch_execz .LBB0_740
	v_cndmask_b32_e64 v55, v42, v46, s[10:11]
	s_nop 1
	v_mov_b32_dpp v55, v55 quad_perm:[1,0,3,2] row_mask:0xf bank_mask:0xf
	v_lshl_add_u64 v[52:53], v[50:51], 1, v[130:131]
	s_mov_b32 s16, 0x12000
	s_waitcnt lgkmcnt(0)
	v_cndmask_b32_e64 v42, v55, v42, s[10:11]
	v_cndmask_b32_e64 v46, v46, v55, s[10:11]
	v_cndmask_b32_e64 v55, v43, v47, s[10:11]
	v_cvt_pk_bf16_f32 v42, v42, v46
	global_store_dword v[52:53], v42, off
	s_nop 1
	v_mov_b32_dpp v42, v55 quad_perm:[1,0,3,2] row_mask:0xf bank_mask:0xf
	v_cndmask_b32_e64 v46, v44, v48, s[10:11]
	s_waitcnt lgkmcnt(0)
	v_cndmask_b32_e64 v43, v42, v43, s[10:11]
	v_cndmask_b32_e64 v42, v47, v42, s[10:11]
	v_cvt_pk_bf16_f32 v47, v43, v42
	v_add_co_u32_e32 v42, vcc, s16, v52
	s_nop 1
	v_addc_co_u32_e32 v43, vcc, 0, v53, vcc
	global_store_dword v[42:43], v47, off
	s_nop 1
	v_mov_b32_dpp v42, v46 quad_perm:[1,0,3,2] row_mask:0xf bank_mask:0xf
	s_waitcnt lgkmcnt(0)
	v_cndmask_b32_e64 v43, v42, v44, s[10:11]
	v_cndmask_b32_e64 v42, v48, v42, s[10:11]
	v_cvt_pk_bf16_f32 v46, v43, v42
	v_add_co_u32_e32 v42, vcc, 0x24000, v52
	v_cndmask_b32_e64 v44, v45, v49, s[10:11]
	s_nop 0
	v_addc_co_u32_e32 v43, vcc, 0, v53, vcc
	global_store_dword v[42:43], v46, off
	s_nop 1
	v_mov_b32_dpp v42, v44 quad_perm:[1,0,3,2] row_mask:0xf bank_mask:0xf
	s_waitcnt lgkmcnt(0)
	v_cndmask_b32_e64 v43, v42, v45, s[10:11]
	v_cndmask_b32_e64 v42, v49, v42, s[10:11]
	v_cvt_pk_bf16_f32 v44, v43, v42
	v_add_co_u32_e32 v42, vcc, 0x36000, v52
	s_nop 1
	v_addc_co_u32_e32 v43, vcc, 0, v53, vcc
	global_store_dword v[42:43], v44, off

; DI unsigned pack2(float a, float b) { f32x2_t v = {a, b}; bf16x2_t r = __builtin_convertvector(v, bf16x2_t); return __builtin_bit_cast(unsigned, r); }
; DI bfu* wsb(const PX& p, size_t off) { return (bfu*)(p.ws + off); }
; template <int EPI, int HM>
; DI void epi256(const PX& p, int l, f32x4 (&acc)[2][2][4][2], int brow, int bcol, int aux, bool src_input) {
;     ...
;           if (EPI == EPI_INPROJ) {
;             if (col0 < 2304) {
;               const bool odd = (fr & 1) != 0;
;               bfu* d = wsb(p, OFF_BIG + B_ZHY) + (size_t)(col0 + (odd ? 4 : 0)) * NTOK + (row & ~1);
; #pragma unroll
;               for (int j = 0; j < 4; j++) {
;                 const float snd = odd ? v[j] : v[4 + j];
;                 const float rcv = __shfl_xor(snd, 1);
;                 const unsigned pr = odd ? pack2(rcv, v[4 + j]) : pack2(v[j], rcv);
;                 *(unsigned*)(d + (size_t)j * NTOK) = pr;
;               }
.LBB0_745:
	s_or_saveexec_b64 s[8:9], s[8:9]
	s_nop 0
	v_and_b32_e32 v42, -2, v46
	v_ashrrev_i32_e32 v43, 31, v42
	s_xor_b64 exec, exec, s[8:9]
	s_cbranch_execz .LBB0_747
	v_cndmask_b32_e64 v47, v34, v38, s[10:11]
	s_nop 1
	v_mov_b32_dpp v47, v47 quad_perm:[1,0,3,2] row_mask:0xf bank_mask:0xf
	v_lshl_add_u64 v[44:45], v[42:43], 1, v[130:131]
	s_mov_b32 s14, 0x12000
	s_waitcnt lgkmcnt(0)
	v_cndmask_b32_e64 v34, v47, v34, s[10:11]
	v_cndmask_b32_e64 v38, v38, v47, s[10:11]
	v_cndmask_b32_e64 v47, v35, v39, s[10:11]
	v_cvt_pk_bf16_f32 v34, v34, v38
	global_store_dword v[44:45], v34, off
	s_nop 1
	v_mov_b32_dpp v34, v47 quad_perm:[1,0,3,2] row_mask:0xf bank_mask:0xf
	v_cndmask_b32_e64 v38, v36, v40, s[10:11]
	s_waitcnt lgkmcnt(0)
	v_cndmask_b32_e64 v35, v34, v35, s[10:11]
	v_cndmask_b32_e64 v34, v39, v34, s[10:11]
	v_cvt_pk_bf16_f32 v39, v35, v34
	v_add_co_u32_e32 v34, vcc, s14, v44
	s_nop 1
	v_addc_co_u32_e32 v35, vcc, 0, v45, vcc
	global_store_dword v[34:35], v39, off
	s_nop 1
	v_mov_b32_dpp v34, v38 quad_perm:[1,0,3,2] row_mask:0xf bank_mask:0xf
	s_waitcnt lgkmcnt(0)
	v_cndmask_b32_e64 v35, v34, v36, s[10:11]
	v_cndmask_b32_e64 v34, v40, v34, s[10:11]
	v_cvt_pk_bf16_f32 v38, v35, v34
	v_add_co_u32_e32 v34, vcc, 0x24000, v44
	v_cndmask_b32_e64 v36, v37, v41, s[10:11]
	s_nop 0
	v_addc_co_u32_e32 v35, vcc, 0, v45, vcc
	global_store_dword v[34:35], v38, off
	s_nop 1
	v_mov_b32_dpp v34, v36 quad_perm:[1,0,3,2] row_mask:0xf bank_mask:0xf
	s_waitcnt lgkmcnt(0)
	v_cndmask_b32_e64 v35, v34, v37, s[10:11]
	v_cndmask_b32_e64 v34, v41, v34, s[10:11]
	v_cvt_pk_bf16_f32 v36, v35, v34
	v_add_co_u32_e32 v34, vcc, 0x36000, v44
	s_nop 1
	v_addc_co_u32_e32 v35, vcc, 0, v45, vcc
	global_store_dword v[34:35], v36, off

; DI unsigned pack2(float a, float b) { f32x2_t v = {a, b}; bf16x2_t r = __builtin_convertvector(v, bf16x2_t); return __builtin_bit_cast(unsigned, r); }
; DI bfu* wsb(const PX& p, size_t off) { return (bfu*)(p.ws + off); }
; template <int EPI, int HM>
; DI void epi256(const PX& p, int l, f32x4 (&acc)[2][2][4][2], int brow, int bcol, int aux, bool src_input) {
;     ...
;           if (EPI == EPI_INPROJ) {
;             if (col0 < 2304) {
;               const bool odd = (fr & 1) != 0;
;               bfu* d = wsb(p, OFF_BIG + B_ZHY) + (size_t)(col0 + (odd ? 4 : 0)) * NTOK + (row & ~1);
; #pragma unroll
;               for (int j = 0; j < 4; j++) {
;                 const float snd = odd ? v[j] : v[4 + j];
;                 const float rcv = __shfl_xor(snd, 1);
;                 const unsigned pr = odd ? pack2(rcv, v[4 + j]) : pack2(v[j], rcv);
;                 *(unsigned*)(d + (size_t)j * NTOK) = pr;
;               }
.LBB0_752:
	s_andn2_saveexec_b64 s[8:9], s[8:9]
	s_cbranch_execz .LBB0_754
	v_cndmask_b32_e64 v36, v26, v30, s[10:11]
	s_nop 1
	v_mov_b32_dpp v36, v36 quad_perm:[1,0,3,2] row_mask:0xf bank_mask:0xf
	v_lshl_add_u64 v[34:35], v[66:67], 1, v[98:99]
	s_mov_b32 s14, 0x12000
	s_waitcnt lgkmcnt(0)
	v_cndmask_b32_e64 v26, v36, v26, s[10:11]
	v_cndmask_b32_e64 v30, v30, v36, s[10:11]
	v_cndmask_b32_e64 v36, v27, v31, s[10:11]
	v_cvt_pk_bf16_f32 v26, v26, v30
	global_store_dword v[34:35], v26, off
	s_nop 1
	v_mov_b32_dpp v26, v36 quad_perm:[1,0,3,2] row_mask:0xf bank_mask:0xf
	v_cndmask_b32_e64 v30, v28, v32, s[10:11]
	s_waitcnt lgkmcnt(0)
	v_cndmask_b32_e64 v27, v26, v27, s[10:11]
	v_cndmask_b32_e64 v26, v31, v26, s[10:11]
	v_cvt_pk_bf16_f32 v31, v27, v26
	v_add_co_u32_e32 v26, vcc, s14, v34
	s_nop 1
	v_addc_co_u32_e32 v27, vcc, 0, v35, vcc
	global_store_dword v[26:27], v31, off
	s_nop 1
	v_mov_b32_dpp v26, v30 quad_perm:[1,0,3,2] row_mask:0xf bank_mask:0xf
	s_waitcnt lgkmcnt(0)
	v_cndmask_b32_e64 v27, v26, v28, s[10:11]
	v_cndmask_b32_e64 v26, v32, v26, s[10:11]
	v_cvt_pk_bf16_f32 v30, v27, v26
	v_add_co_u32_e32 v26, vcc, 0x24000, v34
	v_cndmask_b32_e64 v28, v29, v33, s[10:11]
	s_nop 0
	v_addc_co_u32_e32 v27, vcc, 0, v35, vcc
	global_store_dword v[26:27], v30, off
	s_nop 1
	v_mov_b32_dpp v26, v28 quad_perm:[1,0,3,2] row_mask:0xf bank_mask:0xf
	s_waitcnt lgkmcnt(0)
	v_cndmask_b32_e64 v27, v26, v29, s[10:11]
	v_cndmask_b32_e64 v26, v33, v26, s[10:11]
	v_cvt_pk_bf16_f32 v28, v27, v26
	v_add_co_u32_e32 v26, vcc, 0x36000, v34
	s_nop 1
	v_addc_co_u32_e32 v27, vcc, 0, v35, vcc
	global_store_dword v[26:27], v28, off

; DI unsigned pack2(float a, float b) { f32x2_t v = {a, b}; bf16x2_t r = __builtin_convertvector(v, bf16x2_t); return __builtin_bit_cast(unsigned, r); }
; DI bfu* wsb(const PX& p, size_t off) { return (bfu*)(p.ws + off); }
; template <int EPI, int HM>
; DI void epi256(const PX& p, int l, f32x4 (&acc)[2][2][4][2], int brow, int bcol, int aux, bool src_input) {
;     ...
;           if (EPI == EPI_INPROJ) {
;             if (col0 < 2304) {
;               const bool odd = (fr & 1) != 0;
;               bfu* d = wsb(p, OFF_BIG + B_ZHY) + (size_t)(col0 + (odd ? 4 : 0)) * NTOK + (row & ~1);
; #pragma unroll
;               for (int j = 0; j < 4; j++) {
;                 const float snd = odd ? v[j] : v[4 + j];
;                 const float rcv = __shfl_xor(snd, 1);
;                 const unsigned pr = odd ? pack2(rcv, v[4 + j]) : pack2(v[j], rcv);
;                 *(unsigned*)(d + (size_t)j * NTOK) = pr;
;               }
.LBB0_759:
	s_andn2_saveexec_b64 s[8:9], s[8:9]
	s_cbranch_execz .LBB0_761
	v_cndmask_b32_e64 v28, v18, v22, s[10:11]
	s_nop 1
	v_mov_b32_dpp v28, v28 quad_perm:[1,0,3,2] row_mask:0xf bank_mask:0xf
	v_lshl_add_u64 v[26:27], v[58:59], 1, v[98:99]
	s_mov_b32 s14, 0x12000
	s_waitcnt lgkmcnt(0)
	v_cndmask_b32_e64 v18, v28, v18, s[10:11]
	v_cndmask_b32_e64 v22, v22, v28, s[10:11]
	v_cndmask_b32_e64 v28, v19, v23, s[10:11]
	v_cvt_pk_bf16_f32 v18, v18, v22
	global_store_dword v[26:27], v18, off
	s_nop 1
	v_mov_b32_dpp v18, v28 quad_perm:[1,0,3,2] row_mask:0xf bank_mask:0xf
	v_cndmask_b32_e64 v22, v20, v24, s[10:11]
	s_waitcnt lgkmcnt(0)
	v_cndmask_b32_e64 v19, v18, v19, s[10:11]
	v_cndmask_b32_e64 v18, v23, v18, s[10:11]
	v_cvt_pk_bf16_f32 v23, v19, v18
	v_add_co_u32_e32 v18, vcc, s14, v26
	s_nop 1
	v_addc_co_u32_e32 v19, vcc, 0, v27, vcc
	global_store_dword v[18:19], v23, off
	s_nop 1
	v_mov_b32_dpp v18, v22 quad_perm:[1,0,3,2] row_mask:0xf bank_mask:0xf
	s_waitcnt lgkmcnt(0)
	v_cndmask_b32_e64 v19, v18, v20, s[10:11]
	v_cndmask_b32_e64 v18, v24, v18, s[10:11]
	v_cvt_pk_bf16_f32 v22, v19, v18
	v_add_co_u32_e32 v18, vcc, 0x24000, v26
	v_cndmask_b32_e64 v20, v21, v25, s[10:11]
	s_nop 0
	v_addc_co_u32_e32 v19, vcc, 0, v27, vcc
	global_store_dword v[18:19], v22, off
	s_nop 1
	v_mov_b32_dpp v18, v20 quad_perm:[1,0,3,2] row_mask:0xf bank_mask:0xf
	s_waitcnt lgkmcnt(0)
	v_cndmask_b32_e64 v19, v18, v21, s[10:11]
	v_cndmask_b32_e64 v18, v25, v18, s[10:11]
	v_cvt_pk_bf16_f32 v20, v19, v18
	v_add_co_u32_e32 v18, vcc, 0x36000, v26
	s_nop 1
	v_addc_co_u32_e32 v19, vcc, 0, v27, vcc
	global_store_dword v[18:19], v20, off

; DI unsigned pack2(float a, float b) { f32x2_t v = {a, b}; bf16x2_t r = __builtin_convertvector(v, bf16x2_t); return __builtin_bit_cast(unsigned, r); }
; DI bfu* wsb(const PX& p, size_t off) { return (bfu*)(p.ws + off); }
; template <int EPI, int HM>
; DI void epi256(const PX& p, int l, f32x4 (&acc)[2][2][4][2], int brow, int bcol, int aux, bool src_input) {
;     ...
;           if (EPI == EPI_INPROJ) {
;             if (col0 < 2304) {
;               const bool odd = (fr & 1) != 0;
;               bfu* d = wsb(p, OFF_BIG + B_ZHY) + (size_t)(col0 + (odd ? 4 : 0)) * NTOK + (row & ~1);
; #pragma unroll
;               for (int j = 0; j < 4; j++) {
;                 const float snd = odd ? v[j] : v[4 + j];
;                 const float rcv = __shfl_xor(snd, 1);
;                 const unsigned pr = odd ? pack2(rcv, v[4 + j]) : pack2(v[j], rcv);
;                 *(unsigned*)(d + (size_t)j * NTOK) = pr;
;               }
.LBB0_766:
	s_andn2_saveexec_b64 s[8:9], s[8:9]
	s_cbranch_execz .LBB0_768
	v_cndmask_b32_e64 v20, v10, v14, s[10:11]
	s_nop 1
	v_mov_b32_dpp v20, v20 quad_perm:[1,0,3,2] row_mask:0xf bank_mask:0xf
	v_lshl_add_u64 v[18:19], v[50:51], 1, v[98:99]
	s_mov_b32 s14, 0x12000
	s_waitcnt lgkmcnt(0)
	v_cndmask_b32_e64 v10, v20, v10, s[10:11]
	v_cndmask_b32_e64 v14, v14, v20, s[10:11]
	v_cndmask_b32_e64 v20, v11, v15, s[10:11]
	v_cvt_pk_bf16_f32 v10, v10, v14
	global_store_dword v[18:19], v10, off
	s_nop 1
	v_mov_b32_dpp v10, v20 quad_perm:[1,0,3,2] row_mask:0xf bank_mask:0xf
	v_cndmask_b32_e64 v14, v12, v16, s[10:11]
	s_waitcnt lgkmcnt(0)
	v_cndmask_b32_e64 v11, v10, v11, s[10:11]
	v_cndmask_b32_e64 v10, v15, v10, s[10:11]
	v_cvt_pk_bf16_f32 v15, v11, v10
	v_add_co_u32_e32 v10, vcc, s14, v18
	s_nop 1
	v_addc_co_u32_e32 v11, vcc, 0, v19, vcc
	global_store_dword v[10:11], v15, off
	s_nop 1
	v_mov_b32_dpp v10, v14 quad_perm:[1,0,3,2] row_mask:0xf bank_mask:0xf
	s_waitcnt lgkmcnt(0)
	v_cndmask_b32_e64 v11, v10, v12, s[10:11]
	v_cndmask_b32_e64 v10, v16, v10, s[10:11]
	v_cvt_pk_bf16_f32 v14, v11, v10
	v_add_co_u32_e32 v10, vcc, 0x24000, v18
	v_cndmask_b32_e64 v12, v13, v17, s[10:11]
	s_nop 0
	v_addc_co_u32_e32 v11, vcc, 0, v19, vcc
	global_store_dword v[10:11], v14, off
	s_nop 1
	v_mov_b32_dpp v10, v12 quad_perm:[1,0,3,2] row_mask:0xf bank_mask:0xf
	s_waitcnt lgkmcnt(0)
	v_cndmask_b32_e64 v11, v10, v13, s[10:11]
	v_cndmask_b32_e64 v10, v17, v10, s[10:11]
	v_cvt_pk_bf16_f32 v12, v11, v10
	v_add_co_u32_e32 v10, vcc, 0x36000, v18
	s_nop 1
	v_addc_co_u32_e32 v11, vcc, 0, v19, vcc
	global_store_dword v[10:11], v12, off

; DI unsigned pack2(float a, float b) { f32x2_t v = {a, b}; bf16x2_t r = __builtin_convertvector(v, bf16x2_t); return __builtin_bit_cast(unsigned, r); }
; DI bfu* wsb(const PX& p, size_t off) { return (bfu*)(p.ws + off); }
; template <int EPI, int HM>
; DI void epi256(const PX& p, int l, f32x4 (&acc)[2][2][4][2], int brow, int bcol, int aux, bool src_input) {
;     ...
;           if (EPI == EPI_INPROJ) {
;             if (col0 < 2304) {
;               const bool odd = (fr & 1) != 0;
;               bfu* d = wsb(p, OFF_BIG + B_ZHY) + (size_t)(col0 + (odd ? 4 : 0)) * NTOK + (row & ~1);
; #pragma unroll
;               for (int j = 0; j < 4; j++) {
;                 const float snd = odd ? v[j] : v[4 + j];
;                 const float rcv = __shfl_xor(snd, 1);
;                 const unsigned pr = odd ? pack2(rcv, v[4 + j]) : pack2(v[j], rcv);
;                 *(unsigned*)(d + (size_t)j * NTOK) = pr;
;               }
.LBB0_773:
	s_andn2_saveexec_b64 s[4:5], s[6:7]
	s_cbranch_execz .LBB0_652
	v_cndmask_b32_e64 v0, v2, v6, s[10:11]
	s_nop 1
	v_mov_b32_dpp v0, v0 quad_perm:[1,0,3,2] row_mask:0xf bank_mask:0xf
	v_lshl_add_u64 v[10:11], v[42:43], 1, v[98:99]
	s_mov_b32 s6, 0x12000
	s_waitcnt lgkmcnt(0)
	v_cndmask_b32_e64 v2, v0, v2, s[10:11]
	v_cndmask_b32_e64 v0, v6, v0, s[10:11]
	v_cndmask_b32_e64 v6, v3, v7, s[10:11]
	v_cvt_pk_bf16_f32 v0, v2, v0
	global_store_dword v[10:11], v0, off
	s_nop 1
	v_mov_b32_dpp v0, v6 quad_perm:[1,0,3,2] row_mask:0xf bank_mask:0xf
	v_cndmask_b32_e64 v6, v4, v8, s[10:11]
	s_waitcnt lgkmcnt(0)
	v_cndmask_b32_e64 v2, v0, v3, s[10:11]
	v_cndmask_b32_e64 v0, v7, v0, s[10:11]
	v_cvt_pk_bf16_f32 v0, v2, v0
	v_add_co_u32_e32 v2, vcc, s6, v10
	s_nop 1
	v_addc_co_u32_e32 v3, vcc, 0, v11, vcc
	global_store_dword v[2:3], v0, off
	s_nop 1
	v_mov_b32_dpp v0, v6 quad_perm:[1,0,3,2] row_mask:0xf bank_mask:0xf
	s_waitcnt lgkmcnt(0)
	v_cndmask_b32_e64 v2, v0, v4, s[10:11]
	v_cndmask_b32_e64 v0, v8, v0, s[10:11]
	v_cvt_pk_bf16_f32 v0, v2, v0
	v_add_co_u32_e32 v2, vcc, 0x24000, v10
	v_cndmask_b32_e64 v4, v5, v9, s[10:11]
	s_nop 0
	v_addc_co_u32_e32 v3, vcc, 0, v11, vcc
	global_store_dword v[2:3], v0, off
	s_nop 1
	v_mov_b32_dpp v0, v4 quad_perm:[1,0,3,2] row_mask:0xf bank_mask:0xf
	s_waitcnt lgkmcnt(0)
	v_cndmask_b32_e64 v2, v0, v5, s[10:11]
	v_cndmask_b32_e64 v0, v9, v0, s[10:11]
	v_cvt_pk_bf16_f32 v0, v2, v0
	v_add_co_u32_e32 v2, vcc, 0x36000, v10
	s_nop 1
	v_addc_co_u32_e32 v3, vcc, 0, v11, vcc
	global_store_dword v[2:3], v0, off
	s_branch .LBB0_652
